# grid barrier: waiters poll the monotonic TOP arrival counter (released iff TOP >= nx*(gen+1)) instead of the TOPGEN word, removing the last leader's publish hop
# speedup vs baseline: 1.0107x; 1.0014x over previous
; __device__ __forceinline__ unsigned xb_ld(unsigned* p)              { return __hip_atomic_load(p, __ATOMIC_RELAXED, __HIP_MEMORY_SCOPE_AGENT); }
; __device__ __forceinline__ unsigned xb_add(unsigned* p, unsigned v) { return __hip_atomic_fetch_add(p, v, __ATOMIC_RELAXED, __HIP_MEMORY_SCOPE_AGENT); }
; #define XB_SPIN(cond, bar) do { unsigned _sp = 0; while (cond) { __builtin_amdgcn_s_sleep(0); \
;     if ((++_sp & 255u) == 0u) { if (xb_ld(&(bar)[XB_TMO])) break; if (_sp > XB_SPIN_CAP) { atomicAdd(&(bar)[XB_TMO], 1u); break; } } } } while (0)
; __device__ __forceinline__ void xcd_barrier(const XcdBarrier& b) {
;     ...
;         const unsigned old = xb_add(&bar[XB_XSUB(b.x)], 1u);
;         const unsigned gen = old / nloc;
;         if (old + 1u == (gen + 1u) * nloc) {
;     ...
;             XB_SPIN(xb_ld(&bar[XB_XGEN(b.x)]) == gen, bar);
.LBB0_155:
	s_or_b64 exec, exec, s[0:1]
	v_cvt_f32_u32_e32 v4, v2
	s_waitcnt vmcnt(0)
	v_readfirstlane_b32 s0, v3
	v_sub_u32_e32 v3, 0, v2
	v_rcp_iflag_f32_e32 v4, v4
	v_add_u32_e32 v5, s0, v1
	v_mul_f32_e32 v4, 0x4f7ffffe, v4
	v_cvt_u32_f32_e32 v4, v4
	v_mul_lo_u32 v1, v3, v4
	v_mul_hi_u32 v1, v4, v1
	v_add_u32_e32 v1, v4, v1
	v_mul_hi_u32 v1, v5, v1
	v_mul_lo_u32 v3, v1, v2
	v_sub_u32_e32 v3, v5, v3
	v_add_u32_e32 v4, 1, v1
	v_cmp_ge_u32_e32 vcc, v3, v2
	s_nop 1
	v_cndmask_b32_e32 v1, v1, v4, vcc
	v_sub_u32_e32 v4, v3, v2
	v_cndmask_b32_e32 v3, v3, v4, vcc
	v_add_u32_e32 v4, 1, v1
	v_cmp_ge_u32_e32 vcc, v3, v2
	v_add_u32_e32 v3, 1, v5
	s_nop 0
	v_cndmask_b32_e32 v1, v1, v4, vcc
	v_mul_lo_u32 v4, v2, v1
	v_add_u32_e32 v2, v4, v2
	v_cmp_ne_u32_e32 vcc, v3, v2
	s_and_saveexec_b64 s[0:1], vcc
	s_xor_b64 s[0:1], exec, s[0:1]
	s_cbranch_execz .LBB0_169
	v_readlane_b32 s2, v252, 7
	v_readlane_b32 s3, v252, 8
	s_waitcnt lgkmcnt(0)
	v_mad_u32_u24 v1, v0, v1, v0
	s_nop 3
	global_load_dword v0, v17, s[2:3] sc1
	s_waitcnt vmcnt(0)
	v_cmp_lt_u32_e32 vcc, v0, v1
	s_and_saveexec_b64 s[2:3], vcc
	s_cbranch_execz .LBB0_168
	s_mov_b32 s17, 1
	s_mov_b64 s[6:7], 0
	s_branch .LBB0_159

; __device__ __forceinline__ unsigned xb_ld(unsigned* p)              { return __hip_atomic_load(p, __ATOMIC_RELAXED, __HIP_MEMORY_SCOPE_AGENT); }
; #define XB_SPIN(cond, bar) do { unsigned _sp = 0; while (cond) { __builtin_amdgcn_s_sleep(0); \
;     if ((++_sp & 255u) == 0u) { if (xb_ld(&(bar)[XB_TMO])) break; if (_sp > XB_SPIN_CAP) { atomicAdd(&(bar)[XB_TMO], 1u); break; } } } } while (0)
; __device__ __forceinline__ void xcd_barrier(const XcdBarrier& b) {
;     ...
;             XB_SPIN(xb_ld(&bar[XB_XGEN(b.x)]) == gen, bar);
.LBB0_163:
	v_readlane_b32 s10, v252, 7
	v_readlane_b32 s11, v252, 8
	s_add_i32 s17, s17, 1
	s_mov_b64 s[12:13], -1
	s_nop 2
	global_load_dword v0, v17, s[10:11] sc1
	s_waitcnt vmcnt(0)
	v_cmp_ge_u32_e32 vcc, v0, v1
	s_orn2_b64 s[10:11], vcc, exec
	s_branch .LBB0_158

; __device__ __forceinline__ unsigned xb_ld(unsigned* p)              { return __hip_atomic_load(p, __ATOMIC_RELAXED, __HIP_MEMORY_SCOPE_AGENT); }
; __device__ __forceinline__ unsigned xb_add(unsigned* p, unsigned v) { return __hip_atomic_fetch_add(p, v, __ATOMIC_RELAXED, __HIP_MEMORY_SCOPE_AGENT); }
; #define XB_SPIN(cond, bar) do { unsigned _sp = 0; while (cond) { __builtin_amdgcn_s_sleep(0); \
;     if ((++_sp & 255u) == 0u) { if (xb_ld(&(bar)[XB_TMO])) break; if (_sp > XB_SPIN_CAP) { atomicAdd(&(bar)[XB_TMO], 1u); break; } } } } while (0)
; __device__ __forceinline__ void xcd_barrier(const XcdBarrier& b) {
;     ...
;             const unsigned og = xb_add(&bar[XB_TOP], 1u);
;             const unsigned tg = og / nx;
;             if (og + 1u == (tg + 1u) * nx) xb_add(&bar[XB_TOPGEN], 1u);
;             else XB_SPIN(xb_ld(&bar[XB_TOPGEN]) == tg, bar);
.LBB0_172:
	s_or_b64 exec, exec, s[2:3]
	v_cvt_f32_u32_e32 v3, v0
	s_waitcnt vmcnt(0)
	v_readfirstlane_b32 s0, v2
	s_mov_b64 s[2:3], -1
	v_rcp_iflag_f32_e32 v3, v3
	v_add_u32_e32 v1, s0, v1
	v_add_u32_e32 v4, 1, v1
	v_readlane_b32 s0, v252, 9
	v_mul_f32_e32 v2, 0x4f7ffffe, v3
	v_cvt_u32_f32_e32 v2, v2
	v_sub_u32_e32 v3, 0, v0
	v_readlane_b32 s1, v252, 10
	v_mul_lo_u32 v3, v3, v2
	v_mul_hi_u32 v3, v2, v3
	v_add_u32_e32 v2, v2, v3
	v_mul_hi_u32 v2, v1, v2
	v_mul_lo_u32 v3, v2, v0
	v_sub_u32_e32 v1, v1, v3
	v_add_u32_e32 v5, 1, v2
	v_cmp_ge_u32_e32 vcc, v1, v0
	v_sub_u32_e32 v3, v1, v0
	s_nop 0
	v_cndmask_b32_e32 v2, v2, v5, vcc
	v_cndmask_b32_e32 v1, v1, v3, vcc
	v_add_u32_e32 v3, 1, v2
	v_cmp_ge_u32_e32 vcc, v1, v0
	s_nop 1
	v_cndmask_b32_e32 v2, v2, v3, vcc
	v_mul_lo_u32 v1, v0, v2
	v_add_u32_e32 v0, v1, v0
	v_cmp_ne_u32_e32 vcc, v4, v0
	v_mov_b32_e32 v5, v0
	v_mov_b64_e32 v[0:1], s[0:1]
	s_and_saveexec_b64 s[0:1], vcc
	s_cbranch_execz .LBB0_184
	v_readlane_b32 s2, v252, 7
	v_readlane_b32 s3, v252, 8
	s_mov_b64 s[6:7], 0
	s_nop 3
	global_load_dword v0, v17, s[2:3] sc1
	s_waitcnt vmcnt(0)
	v_cmp_lt_u32_e32 vcc, v0, v5
	s_and_saveexec_b64 s[2:3], vcc
	s_cbranch_execz .LBB0_183
	s_mov_b32 s17, 1
	s_branch .LBB0_176

; __device__ __forceinline__ unsigned xb_ld(unsigned* p)              { return __hip_atomic_load(p, __ATOMIC_RELAXED, __HIP_MEMORY_SCOPE_AGENT); }
; #define XB_SPIN(cond, bar) do { unsigned _sp = 0; while (cond) { __builtin_amdgcn_s_sleep(0); \
;     if ((++_sp & 255u) == 0u) { if (xb_ld(&(bar)[XB_TMO])) break; if (_sp > XB_SPIN_CAP) { atomicAdd(&(bar)[XB_TMO], 1u); break; } } } } while (0)
; __device__ __forceinline__ void xcd_barrier(const XcdBarrier& b) {
;     ...
;             else XB_SPIN(xb_ld(&bar[XB_TOPGEN]) == tg, bar);
.LBB0_180:
	v_readlane_b32 s10, v252, 7
	v_readlane_b32 s11, v252, 8
	s_add_i32 s17, s17, 1
	s_mov_b64 s[12:13], -1
	s_nop 2
	global_load_dword v0, v17, s[10:11] sc1
	s_waitcnt vmcnt(0)
	v_cmp_ge_u32_e32 vcc, v0, v5
	s_orn2_b64 s[10:11], vcc, exec
	s_branch .LBB0_175

; __device__ __forceinline__ unsigned xb_ld(unsigned* p)              { return __hip_atomic_load(p, __ATOMIC_RELAXED, __HIP_MEMORY_SCOPE_AGENT); }
; __device__ __forceinline__ unsigned xb_add(unsigned* p, unsigned v) { return __hip_atomic_fetch_add(p, v, __ATOMIC_RELAXED, __HIP_MEMORY_SCOPE_AGENT); }
; #define XB_SPIN(cond, bar) do { unsigned _sp = 0; while (cond) { __builtin_amdgcn_s_sleep(0); \
;     if ((++_sp & 255u) == 0u) { if (xb_ld(&(bar)[XB_TMO])) break; if (_sp > XB_SPIN_CAP) { atomicAdd(&(bar)[XB_TMO], 1u); break; } } } } while (0)
; __device__ __forceinline__ void xcd_barrier(const XcdBarrier& b) {
;     ...
;         const unsigned old = xb_add(&bar[XB_XSUB(b.x)], 1u);
;         const unsigned gen = old / nloc;
;         if (old + 1u == (gen + 1u) * nloc) {
;     ...
;             XB_SPIN(xb_ld(&bar[XB_XGEN(b.x)]) == gen, bar);
.LBB0_244:
	s_or_b64 exec, exec, s[0:1]
	v_cvt_f32_u32_e32 v4, v2
	s_waitcnt vmcnt(0)
	v_readfirstlane_b32 s0, v3
	v_sub_u32_e32 v3, 0, v2
	v_rcp_iflag_f32_e32 v4, v4
	v_add_u32_e32 v5, s0, v1
	v_mul_f32_e32 v4, 0x4f7ffffe, v4
	v_cvt_u32_f32_e32 v4, v4
	v_mul_lo_u32 v1, v3, v4
	v_mul_hi_u32 v1, v4, v1
	v_add_u32_e32 v1, v4, v1
	v_mul_hi_u32 v1, v5, v1
	v_mul_lo_u32 v3, v1, v2
	v_sub_u32_e32 v3, v5, v3
	v_add_u32_e32 v4, 1, v1
	v_cmp_ge_u32_e32 vcc, v3, v2
	s_nop 1
	v_cndmask_b32_e32 v1, v1, v4, vcc
	v_sub_u32_e32 v4, v3, v2
	v_cndmask_b32_e32 v3, v3, v4, vcc
	v_add_u32_e32 v4, 1, v1
	v_cmp_ge_u32_e32 vcc, v3, v2
	v_add_u32_e32 v3, 1, v5
	s_nop 0
	v_cndmask_b32_e32 v1, v1, v4, vcc
	v_mul_lo_u32 v4, v2, v1
	v_add_u32_e32 v2, v4, v2
	v_cmp_ne_u32_e32 vcc, v3, v2
	s_and_saveexec_b64 s[0:1], vcc
	s_xor_b64 s[0:1], exec, s[0:1]
	s_cbranch_execz .LBB0_258
	v_readlane_b32 s2, v252, 7
	v_readlane_b32 s3, v252, 8
	s_waitcnt lgkmcnt(0)
	v_mad_u32_u24 v1, v0, v1, v0
	s_nop 3
	global_load_dword v0, v17, s[2:3] sc1
	s_waitcnt vmcnt(0)
	v_cmp_lt_u32_e32 vcc, v0, v1
	s_and_saveexec_b64 s[2:3], vcc
	s_cbranch_execz .LBB0_257
	s_mov_b32 s19, 1
	s_mov_b64 s[8:9], 0
	s_branch .LBB0_248

; __device__ __forceinline__ unsigned xb_ld(unsigned* p)              { return __hip_atomic_load(p, __ATOMIC_RELAXED, __HIP_MEMORY_SCOPE_AGENT); }
; #define XB_SPIN(cond, bar) do { unsigned _sp = 0; while (cond) { __builtin_amdgcn_s_sleep(0); \
;     if ((++_sp & 255u) == 0u) { if (xb_ld(&(bar)[XB_TMO])) break; if (_sp > XB_SPIN_CAP) { atomicAdd(&(bar)[XB_TMO], 1u); break; } } } } while (0)
; __device__ __forceinline__ void xcd_barrier(const XcdBarrier& b) {
;     ...
;             XB_SPIN(xb_ld(&bar[XB_XGEN(b.x)]) == gen, bar);
.LBB0_252:
	v_readlane_b32 s12, v252, 7
	v_readlane_b32 s13, v252, 8
	s_add_i32 s19, s19, 1
	s_mov_b64 s[14:15], -1
	s_nop 2
	global_load_dword v0, v17, s[12:13] sc1
	s_waitcnt vmcnt(0)
	v_cmp_ge_u32_e32 vcc, v0, v1
	s_orn2_b64 s[12:13], vcc, exec
	s_branch .LBB0_247

; __device__ __forceinline__ unsigned xb_ld(unsigned* p)              { return __hip_atomic_load(p, __ATOMIC_RELAXED, __HIP_MEMORY_SCOPE_AGENT); }
; __device__ __forceinline__ unsigned xb_add(unsigned* p, unsigned v) { return __hip_atomic_fetch_add(p, v, __ATOMIC_RELAXED, __HIP_MEMORY_SCOPE_AGENT); }
; #define XB_SPIN(cond, bar) do { unsigned _sp = 0; while (cond) { __builtin_amdgcn_s_sleep(0); \
;     if ((++_sp & 255u) == 0u) { if (xb_ld(&(bar)[XB_TMO])) break; if (_sp > XB_SPIN_CAP) { atomicAdd(&(bar)[XB_TMO], 1u); break; } } } } while (0)
; __device__ __forceinline__ void xcd_barrier(const XcdBarrier& b) {
;     ...
;             const unsigned og = xb_add(&bar[XB_TOP], 1u);
;             const unsigned tg = og / nx;
;             if (og + 1u == (tg + 1u) * nx) xb_add(&bar[XB_TOPGEN], 1u);
;             else XB_SPIN(xb_ld(&bar[XB_TOPGEN]) == tg, bar);
.LBB0_261:
	s_or_b64 exec, exec, s[2:3]
	s_waitcnt vmcnt(0)
	v_readfirstlane_b32 s0, v2
	v_cvt_f32_u32_e32 v2, v0
	v_sub_u32_e32 v3, 0, v0
	v_add_u32_e32 v1, s0, v1
	v_readlane_b32 s0, v252, 9
	v_rcp_iflag_f32_e32 v2, v2
	v_readlane_b32 s1, v252, 10
	s_mov_b64 s[2:3], -1
	v_mul_f32_e32 v2, 0x4f7ffffe, v2
	v_cvt_u32_f32_e32 v2, v2
	v_mul_lo_u32 v3, v3, v2
	v_mul_hi_u32 v3, v2, v3
	v_add_u32_e32 v2, v2, v3
	v_mul_hi_u32 v2, v1, v2
	v_mul_lo_u32 v3, v2, v0
	v_sub_u32_e32 v3, v1, v3
	v_cmp_ge_u32_e32 vcc, v3, v0
	v_add_u32_e32 v4, 1, v2
	v_add_u32_e32 v1, 1, v1
	v_cndmask_b32_e32 v2, v2, v4, vcc
	v_sub_u32_e32 v4, v3, v0
	v_cndmask_b32_e32 v3, v3, v4, vcc
	v_cmp_ge_u32_e32 vcc, v3, v0
	v_add_u32_e32 v3, 1, v2
	s_nop 0
	v_cndmask_b32_e32 v2, v2, v3, vcc
	v_mul_lo_u32 v3, v0, v2
	v_add_u32_e32 v0, v3, v0
	v_cmp_ne_u32_e32 vcc, v1, v0
	v_mov_b32_e32 v5, v0
	v_mov_b64_e32 v[0:1], s[0:1]
	s_and_saveexec_b64 s[0:1], vcc
	s_cbranch_execz .LBB0_273
	v_readlane_b32 s2, v252, 7
	v_readlane_b32 s3, v252, 8
	s_mov_b64 s[8:9], 0
	s_nop 3
	global_load_dword v0, v17, s[2:3] sc1
	s_waitcnt vmcnt(0)
	v_cmp_lt_u32_e32 vcc, v0, v5
	s_and_saveexec_b64 s[2:3], vcc
	s_cbranch_execz .LBB0_272
	s_mov_b32 s19, 1
	s_branch .LBB0_265

; __device__ __forceinline__ unsigned xb_ld(unsigned* p)              { return __hip_atomic_load(p, __ATOMIC_RELAXED, __HIP_MEMORY_SCOPE_AGENT); }
; #define XB_SPIN(cond, bar) do { unsigned _sp = 0; while (cond) { __builtin_amdgcn_s_sleep(0); \
;     if ((++_sp & 255u) == 0u) { if (xb_ld(&(bar)[XB_TMO])) break; if (_sp > XB_SPIN_CAP) { atomicAdd(&(bar)[XB_TMO], 1u); break; } } } } while (0)
; __device__ __forceinline__ void xcd_barrier(const XcdBarrier& b) {
;     ...
;             else XB_SPIN(xb_ld(&bar[XB_TOPGEN]) == tg, bar);
.LBB0_269:
	v_readlane_b32 s12, v252, 7
	v_readlane_b32 s13, v252, 8
	s_add_i32 s19, s19, 1
	s_mov_b64 s[14:15], -1
	s_nop 2
	global_load_dword v0, v17, s[12:13] sc1
	s_waitcnt vmcnt(0)
	v_cmp_ge_u32_e32 vcc, v0, v5
	s_orn2_b64 s[12:13], vcc, exec
	s_branch .LBB0_264

; __device__ __forceinline__ unsigned xb_ld(unsigned* p)              { return __hip_atomic_load(p, __ATOMIC_RELAXED, __HIP_MEMORY_SCOPE_AGENT); }
; __device__ __forceinline__ unsigned xb_add(unsigned* p, unsigned v) { return __hip_atomic_fetch_add(p, v, __ATOMIC_RELAXED, __HIP_MEMORY_SCOPE_AGENT); }
; #define XB_SPIN(cond, bar) do { unsigned _sp = 0; while (cond) { __builtin_amdgcn_s_sleep(0); \
;     if ((++_sp & 255u) == 0u) { if (xb_ld(&(bar)[XB_TMO])) break; if (_sp > XB_SPIN_CAP) { atomicAdd(&(bar)[XB_TMO], 1u); break; } } } } while (0)
; __device__ __forceinline__ void xcd_barrier(const XcdBarrier& b) {
;     ...
;         const unsigned old = xb_add(&bar[XB_XSUB(b.x)], 1u);
;         const unsigned gen = old / nloc;
;         if (old + 1u == (gen + 1u) * nloc) {
;     ...
;             XB_SPIN(xb_ld(&bar[XB_XGEN(b.x)]) == gen, bar);
.LBB0_1997:
	s_or_b64 exec, exec, s[0:1]
	v_cvt_f32_u32_e32 v4, v2
	s_waitcnt vmcnt(0)
	v_readfirstlane_b32 s0, v3
	v_sub_u32_e32 v3, 0, v2
	v_rcp_iflag_f32_e32 v4, v4
	v_add_u32_e32 v5, s0, v1
	v_mul_f32_e32 v4, 0x4f7ffffe, v4
	v_cvt_u32_f32_e32 v4, v4
	v_mul_lo_u32 v1, v3, v4
	v_mul_hi_u32 v1, v4, v1
	v_add_u32_e32 v1, v4, v1
	v_mul_hi_u32 v1, v5, v1
	v_mul_lo_u32 v3, v1, v2
	v_sub_u32_e32 v3, v5, v3
	v_add_u32_e32 v4, 1, v1
	v_cmp_ge_u32_e32 vcc, v3, v2
	s_nop 1
	v_cndmask_b32_e32 v1, v1, v4, vcc
	v_sub_u32_e32 v4, v3, v2
	v_cndmask_b32_e32 v3, v3, v4, vcc
	v_add_u32_e32 v4, 1, v1
	v_cmp_ge_u32_e32 vcc, v3, v2
	v_add_u32_e32 v3, 1, v5
	s_nop 0
	v_cndmask_b32_e32 v1, v1, v4, vcc
	v_mul_lo_u32 v4, v2, v1
	v_add_u32_e32 v2, v4, v2
	v_cmp_ne_u32_e32 vcc, v3, v2
	s_and_saveexec_b64 s[0:1], vcc
	s_xor_b64 s[0:1], exec, s[0:1]
	s_cbranch_execz .LBB0_2011
	v_readlane_b32 s2, v252, 7
	v_readlane_b32 s3, v252, 8
	s_waitcnt lgkmcnt(0)
	v_mad_u32_u24 v1, v0, v1, v0
	s_nop 3
	global_load_dword v0, v17, s[2:3] sc1
	s_waitcnt vmcnt(0)
	v_cmp_lt_u32_e32 vcc, v0, v1
	s_and_saveexec_b64 s[2:3], vcc
	s_cbranch_execz .LBB0_2010
	s_mov_b32 s16, 1
	s_mov_b64 s[6:7], 0
	s_branch .LBB0_2001

; __device__ __forceinline__ unsigned xb_ld(unsigned* p)              { return __hip_atomic_load(p, __ATOMIC_RELAXED, __HIP_MEMORY_SCOPE_AGENT); }
; #define XB_SPIN(cond, bar) do { unsigned _sp = 0; while (cond) { __builtin_amdgcn_s_sleep(0); \
;     if ((++_sp & 255u) == 0u) { if (xb_ld(&(bar)[XB_TMO])) break; if (_sp > XB_SPIN_CAP) { atomicAdd(&(bar)[XB_TMO], 1u); break; } } } } while (0)
; __device__ __forceinline__ void xcd_barrier(const XcdBarrier& b) {
;     ...
;             XB_SPIN(xb_ld(&bar[XB_XGEN(b.x)]) == gen, bar);
.LBB0_2005:
	v_readlane_b32 s10, v252, 7
	v_readlane_b32 s11, v252, 8
	s_add_i32 s16, s16, 1
	s_mov_b64 s[12:13], -1
	s_nop 2
	global_load_dword v0, v17, s[10:11] sc1
	s_waitcnt vmcnt(0)
	v_cmp_ge_u32_e32 vcc, v0, v1
	s_orn2_b64 s[10:11], vcc, exec
	s_branch .LBB0_2000

; __device__ __forceinline__ unsigned xb_ld(unsigned* p)              { return __hip_atomic_load(p, __ATOMIC_RELAXED, __HIP_MEMORY_SCOPE_AGENT); }
; __device__ __forceinline__ unsigned xb_add(unsigned* p, unsigned v) { return __hip_atomic_fetch_add(p, v, __ATOMIC_RELAXED, __HIP_MEMORY_SCOPE_AGENT); }
; #define XB_SPIN(cond, bar) do { unsigned _sp = 0; while (cond) { __builtin_amdgcn_s_sleep(0); \
;     if ((++_sp & 255u) == 0u) { if (xb_ld(&(bar)[XB_TMO])) break; if (_sp > XB_SPIN_CAP) { atomicAdd(&(bar)[XB_TMO], 1u); break; } } } } while (0)
; __device__ __forceinline__ void xcd_barrier(const XcdBarrier& b) {
;     ...
;             const unsigned og = xb_add(&bar[XB_TOP], 1u);
;             const unsigned tg = og / nx;
;             if (og + 1u == (tg + 1u) * nx) xb_add(&bar[XB_TOPGEN], 1u);
;             else XB_SPIN(xb_ld(&bar[XB_TOPGEN]) == tg, bar);
.LBB0_2014:
	s_or_b64 exec, exec, s[2:3]
	s_waitcnt vmcnt(0)
	v_readfirstlane_b32 s0, v2
	v_cvt_f32_u32_e32 v2, v0
	v_sub_u32_e32 v3, 0, v0
	v_add_u32_e32 v1, s0, v1
	v_readlane_b32 s0, v252, 9
	v_rcp_iflag_f32_e32 v2, v2
	v_readlane_b32 s1, v252, 10
	s_mov_b64 s[2:3], -1
	v_mul_f32_e32 v2, 0x4f7ffffe, v2
	v_cvt_u32_f32_e32 v2, v2
	v_mul_lo_u32 v3, v3, v2
	v_mul_hi_u32 v3, v2, v3
	v_add_u32_e32 v2, v2, v3
	v_mul_hi_u32 v2, v1, v2
	v_mul_lo_u32 v3, v2, v0
	v_sub_u32_e32 v3, v1, v3
	v_cmp_ge_u32_e32 vcc, v3, v0
	v_add_u32_e32 v4, 1, v2
	v_add_u32_e32 v1, 1, v1
	v_cndmask_b32_e32 v2, v2, v4, vcc
	v_sub_u32_e32 v4, v3, v0
	v_cndmask_b32_e32 v3, v3, v4, vcc
	v_cmp_ge_u32_e32 vcc, v3, v0
	v_add_u32_e32 v3, 1, v2
	s_nop 0
	v_cndmask_b32_e32 v2, v2, v3, vcc
	v_mul_lo_u32 v3, v0, v2
	v_add_u32_e32 v0, v3, v0
	v_cmp_ne_u32_e32 vcc, v1, v0
	v_mov_b32_e32 v5, v0
	v_mov_b64_e32 v[0:1], s[0:1]
	s_and_saveexec_b64 s[0:1], vcc
	s_cbranch_execz .LBB0_2026
	v_readlane_b32 s2, v252, 7
	v_readlane_b32 s3, v252, 8
	s_mov_b64 s[6:7], 0
	s_nop 3
	global_load_dword v0, v17, s[2:3] sc1
	s_waitcnt vmcnt(0)
	v_cmp_lt_u32_e32 vcc, v0, v5
	s_and_saveexec_b64 s[2:3], vcc
	s_cbranch_execz .LBB0_2025
	s_mov_b32 s16, 1
	s_branch .LBB0_2018

; __device__ __forceinline__ unsigned xb_ld(unsigned* p)              { return __hip_atomic_load(p, __ATOMIC_RELAXED, __HIP_MEMORY_SCOPE_AGENT); }
; #define XB_SPIN(cond, bar) do { unsigned _sp = 0; while (cond) { __builtin_amdgcn_s_sleep(0); \
;     if ((++_sp & 255u) == 0u) { if (xb_ld(&(bar)[XB_TMO])) break; if (_sp > XB_SPIN_CAP) { atomicAdd(&(bar)[XB_TMO], 1u); break; } } } } while (0)
; __device__ __forceinline__ void xcd_barrier(const XcdBarrier& b) {
;     ...
;             else XB_SPIN(xb_ld(&bar[XB_TOPGEN]) == tg, bar);
.LBB0_2022:
	v_readlane_b32 s10, v252, 7
	v_readlane_b32 s11, v252, 8
	s_add_i32 s16, s16, 1
	s_mov_b64 s[12:13], -1
	s_nop 2
	global_load_dword v0, v17, s[10:11] sc1
	s_waitcnt vmcnt(0)
	v_cmp_ge_u32_e32 vcc, v0, v5
	s_orn2_b64 s[10:11], vcc, exec
	s_branch .LBB0_2017
